# P3 loop: K-fragment wait split in two (p0 chain starts after the first four reads)
# speedup vs baseline: 1.0076x; 1.0076x over previous
.LBB0_325:
	s_waitcnt lgkmcnt(4)
	v_mfma_f32_32x32x16_bf16 v[96:111], v[80:83], v[144:147], v[64:79]
	v_mfma_f32_32x32x16_bf16 v[96:111], v[202:205], v[140:143], v[96:111]
	v_cvt_f32_i32_e32 v156, s100
	v_mfma_f32_32x32x16_bf16 v[96:111], v[194:197], v[136:139], v[96:111]
	v_fma_f32 v254, v208, v156, -v207
	v_mfma_f32_32x32x16_bf16 v[96:111], v[186:189], v[132:135], v[96:111]
	v_add_f32_e32 v255, v237, v254
	s_add_i32 s3, s79, 0xfffe8000
	s_and_b32 s3, s3, 0x18000
	v_add_u32_e32 v158, s3, v235
	v_add_u32_e32 v159, s3, v239
	v_add_u32_e32 v160, s3, v236
	v_add_u32_e32 v161, s3, v234
	ds_read_b64_tr_b16 v[182:183], v158 offset:32768
	ds_read_b64_tr_b16 v[184:185], v158 offset:34816
	ds_read_b64_tr_b16 v[178:179], v159 offset:32768
	ds_read_b64_tr_b16 v[180:181], v159 offset:34816
	ds_read_b64_tr_b16 v[148:149], v160 offset:32768
	ds_read_b64_tr_b16 v[150:151], v160 offset:34816
	ds_read_b64_tr_b16 v[152:153], v161 offset:32768
	ds_read_b64_tr_b16 v[154:155], v161 offset:34816
	s_waitcnt lgkmcnt(8)
	v_mfma_f32_32x32x16_bf16 v[80:95], v[198:201], v[144:147], v[64:79]
	v_add_f32_e32 v96, v254, v96
	v_exp_f32_e32 v96, v96
	v_add_f32_e32 v97, v254, v97
	v_exp_f32_e32 v97, v97
	v_add_f32_e32 v98, v254, v98
	v_exp_f32_e32 v98, v98
	v_add_f32_e32 v99, v254, v99
	v_exp_f32_e32 v99, v99
	v_mfma_f32_32x32x16_bf16 v[80:95], v[190:193], v[140:143], v[80:95]
	v_add_f32_e32 v100, v254, v100
	v_exp_f32_e32 v100, v100
	v_add_f32_e32 v101, v254, v101
	v_exp_f32_e32 v101, v101
	v_add_f32_e32 v102, v254, v102
	v_exp_f32_e32 v102, v102
	v_add_f32_e32 v103, v254, v103
	v_exp_f32_e32 v103, v103
	v_mfma_f32_32x32x16_bf16 v[80:95], v[246:249], v[136:139], v[80:95]
	v_add_f32_e32 v104, v254, v104
	v_exp_f32_e32 v104, v104
	v_add_f32_e32 v105, v254, v105
	v_exp_f32_e32 v105, v105
	v_add_f32_e32 v106, v254, v106
	v_exp_f32_e32 v106, v106
	v_add_f32_e32 v107, v254, v107
	v_exp_f32_e32 v107, v107
	v_mfma_f32_32x32x16_bf16 v[80:95], v[250:253], v[132:135], v[80:95]
	v_add_f32_e32 v108, v254, v108
	v_exp_f32_e32 v108, v108
	v_add_f32_e32 v109, v254, v109
	v_exp_f32_e32 v109, v109
	v_add_f32_e32 v110, v254, v110
	v_exp_f32_e32 v110, v110
	v_add_f32_e32 v111, v254, v111
	v_exp_f32_e32 v111, v111
	s_cmp_le_i32 s72, s101
	s_cbranch_scc0 .Lmask_blk
